# attention: QK MFMAs of a fully masked second key-half and the matching P.V k-steps are skipped (odd waves' last live tile)
# baseline (speedup 1.0000x reference)
; #define SBAR() __builtin_amdgcn_sched_barrier(0)
; #define QK_RD(d0, sl) do { if ((d0) < 8) { const int a_ = kbase ^ (((d0) & 7) << 5); KRD(f0[sl], a_, 0); KRD(f1[sl], a_, 32 * 256); } \
;                            else { const int a_ = rbase ^ (((d0) & 3) << 5); KRD(f0[sl], a_, 0); KRD(f1[sl], a_, 32 * 128); } } while (0)
; #define PV_RD(d0, L, H) do { constexpr int b_ = v_rd_off(d0, 0, 0); TRRD(L[0], b_); TRRD(H[0], b_ + 2048); TRRD(L[1], b_ + 4096); TRRD(H[1], b_ + 6144); TRRD(L[2], b_ + 8192); TRRD(H[2], b_ + 10240); TRRD(L[3], b_ + 12288); TRRD(H[3], b_ + 14336); } while (0)
; #define LGKM(n) asm volatile("s_waitcnt lgkmcnt(" #n ")" ::: "memory")
; __device__ __forceinline__ void mphase(bool has_pv, f32x16* o, int vb, bf16x8 pa0, bf16x8 pa1, bf16x8 pa2, bf16x8 pa3, f32x16& p0, f32x16& p1, int kbase, int rbase, const bf16x8* qr) {
;     ...
;     if (has_pv) {
;         s16x4 la[4], ha[4], lb[4], hb[4];
;         PV_RD(0, la, ha); PV_RD(1, lb, hb);
;         LGKM(8); SBAR(); PV_MM(0, la, ha); SBAR();
;         PV_RD(2, la, ha); LGKM(8); SBAR(); PV_MM(1, lb, hb); SBAR();
;         PV_RD(3, lb, hb); LGKM(8); SBAR(); PV_MM(2, la, ha); SBAR();
;         LGKM(0); SBAR(); PV_MM(3, lb, hb); SBAR();
;     }
;     QK_RD(0, 0); QK_RD(1, 1);
;     p0 = f32x16{}; p1 = f32x16{};
; #pragma unroll
;     for (int d0 = 0; d0 < 12; ++d0) {
;         if (d0 + 2 < 12) { QK_RD(d0 + 2, (d0 + 2) % 3); LGKM(4); }
;         else if (d0 + 1 < 12) LGKM(2);
;         else LGKM(0);
;         SBAR();
;         p0 = __builtin_amdgcn_mfma_f32_32x32x16_bf16(f0[d0 % 3], qr[d0], p0, 0, 0, 0);
;         p1 = __builtin_amdgcn_mfma_f32_32x32x16_bf16(f1[d0 % 3], qr[d0], p1, 0, 0, 0);
;         SBAR(); }
; __device__ __forceinline__ void attn_block(const Ptrs& P, int b, int h, int qb, LAS char* lds) {
;     ...
;     for (int x = 0; x < NT; ++x) {
;         SBAR(); __builtin_amdgcn_s_setprio(1);
;         mphase(x > 0, o, vb0 + pv3 * SHM_V, pa0, pa1, pa2, pa3, p0, p1, kbase, rbase, qr); if (x > 0) pv3 = pv3 == 2 ? 0 : pv3 + 1;
.LBB0_615:
	s_setprio 1
	s_cmp_eq_u32 s81, 0
	s_cselect_b64 s[56:57], -1, 0
	s_add_i32 s22, s75, s81
	s_cmp_lt_i32 s22, -95
	s_cbranch_scc1 .Lattn_dead_m
	s_and_b64 vcc, exec, s[56:57]
	s_cbranch_vccnz .LBB0_617
	s_cmp_lt_i32 s22, -63
	s_cbranch_scc1 .Lattn_pv_h
	v_lshl_add_u32 v199, s83, 14, v182
	ds_read_b64_tr_b16 v[84:85], v199 offset:0x0
	ds_read_b64_tr_b16 v[86:87], v199 offset:0x800
	ds_read_b64_tr_b16 v[88:89], v199 offset:0x1000
	ds_read_b64_tr_b16 v[90:91], v199 offset:0x1800
	ds_read_b64_tr_b16 v[92:93], v199 offset:0x2000
	ds_read_b64_tr_b16 v[94:95], v199 offset:0x2800
	ds_read_b64_tr_b16 v[96:97], v199 offset:0x3000
	ds_read_b64_tr_b16 v[98:99], v199 offset:0x3800
	s_waitcnt lgkmcnt(6)
	v_mfma_f32_32x32x16_bf16 v[52:67], v[68:71], v[84:87], v[52:67]
	ds_read_b64_tr_b16 v[200:201], v199 offset:0x200
	ds_read_b64_tr_b16 v[202:203], v199 offset:0xa00
	s_waitcnt lgkmcnt(6)
	v_mfma_f32_32x32x16_bf16 v[52:67], v[72:75], v[88:91], v[52:67]
	ds_read_b64_tr_b16 v[204:205], v199 offset:0x1200
	ds_read_b64_tr_b16 v[206:207], v199 offset:0x1a00
	s_waitcnt lgkmcnt(6)
	v_mfma_f32_32x32x16_bf16 v[52:67], v[76:79], v[92:95], v[52:67]
	ds_read_b64_tr_b16 v[208:209], v199 offset:0x2200
	ds_read_b64_tr_b16 v[210:211], v199 offset:0x2a00
	s_waitcnt lgkmcnt(6)
	v_mfma_f32_32x32x16_bf16 v[52:67], v[80:83], v[96:99], v[52:67]
	ds_read_b64_tr_b16 v[212:213], v199 offset:0x3200
	ds_read_b64_tr_b16 v[214:215], v199 offset:0x3a00
	ds_read_b64_tr_b16 v[84:85], v199 offset:0x400
	ds_read_b64_tr_b16 v[86:87], v199 offset:0xc00
	s_waitcnt lgkmcnt(8)
	v_mfma_f32_32x32x16_bf16 v[36:51], v[68:71], v[200:203], v[36:51]
	ds_read_b64_tr_b16 v[88:89], v199 offset:0x1400
	ds_read_b64_tr_b16 v[90:91], v199 offset:0x1c00
	s_waitcnt lgkmcnt(8)
	v_mfma_f32_32x32x16_bf16 v[36:51], v[72:75], v[204:207], v[36:51]
	ds_read_b64_tr_b16 v[92:93], v199 offset:0x2400
	ds_read_b64_tr_b16 v[94:95], v199 offset:0x2c00
	s_waitcnt lgkmcnt(8)
	v_mfma_f32_32x32x16_bf16 v[36:51], v[76:79], v[208:211], v[36:51]
	ds_read_b64_tr_b16 v[96:97], v199 offset:0x3400
	ds_read_b64_tr_b16 v[98:99], v199 offset:0x3c00
	s_waitcnt lgkmcnt(8)
	v_mfma_f32_32x32x16_bf16 v[36:51], v[80:83], v[212:215], v[36:51]
	ds_read_b64_tr_b16 v[200:201], v199 offset:0x600
	ds_read_b64_tr_b16 v[202:203], v199 offset:0xe00
	s_waitcnt lgkmcnt(8)
	v_mfma_f32_32x32x16_bf16 v[20:35], v[68:71], v[84:87], v[20:35]
	ds_read_b64_tr_b16 v[204:205], v199 offset:0x1600
	ds_read_b64_tr_b16 v[206:207], v199 offset:0x1e00
	s_waitcnt lgkmcnt(8)
	v_mfma_f32_32x32x16_bf16 v[20:35], v[72:75], v[88:91], v[20:35]
	ds_read_b64_tr_b16 v[208:209], v199 offset:0x2600
	ds_read_b64_tr_b16 v[210:211], v199 offset:0x2e00
	s_waitcnt lgkmcnt(8)
	v_mfma_f32_32x32x16_bf16 v[20:35], v[76:79], v[92:95], v[20:35]
	ds_read_b64_tr_b16 v[212:213], v199 offset:0x3600
	ds_read_b64_tr_b16 v[214:215], v199 offset:0x3e00
	s_waitcnt lgkmcnt(8)
	v_mfma_f32_32x32x16_bf16 v[20:35], v[80:83], v[96:99], v[20:35]
	s_waitcnt lgkmcnt(6)
	v_mfma_f32_32x32x16_bf16 v[4:19], v[68:71], v[200:203], v[4:19]
	ds_read_b128 v[68:71], v3 offset:0
	s_waitcnt lgkmcnt(5)
	v_mfma_f32_32x32x16_bf16 v[4:19], v[72:75], v[204:207], v[4:19]
	ds_read_b128 v[72:75], v3 offset:0x2000
	v_xor_b32_e32 v199, 32, v3
	ds_read_b128 v[200:203], v199 offset:0
	s_waitcnt lgkmcnt(5)
	v_mfma_f32_32x32x16_bf16 v[4:19], v[76:79], v[208:211], v[4:19]
	ds_read_b128 v[204:207], v199 offset:0x2000
	s_waitcnt lgkmcnt(4)
	v_mfma_f32_32x32x16_bf16 v[4:19], v[80:83], v[212:215], v[4:19]
	v_xor_b32_e32 v76, 64, v3
	ds_read_b128 v[208:211], v76 offset:0
	ds_read_b128 v[212:215], v76 offset:0x2000
	s_cmp_lt_i32 s22, -31
	s_cbranch_scc1 .Lattn_dead_qk
	s_cmp_lt_i32 s22, 1
	s_cbranch_scc1 .Lattn_qk_h
	s_branch .Lattn_qk

; __device__ __forceinline__ void attn_block(const Ptrs& P, int b, int h, int qb, LAS char* lds) {
;     ...
;         { const int kb_ = x * KVBLK; if (kb_ + KVBLK - 1 > qlo) { const int dq = qm - kb_; const float NEG = -__builtin_inff();
; #pragma unroll
;             for (int r = 0; r < 16; ++r) { const int c_ = (r & 3) + 8 * (r >> 2); if (dq - c_ < 0) p0[r] = NEG; if (dq - c_ - 32 < 0) p1[r] = NEG; } } }
.Lattn_qk_end:
	s_setprio 0
	s_cmp_le_u32 s82, s75
	s_barrier
	s_cbranch_scc1 .LBB0_619
	v_add_u32_e32 v199, s81, v195
	s_nop 3
	v_cmp_gt_i32_e64 s[22:23], -16, v199
	v_cmp_gt_i32_e64 s[98:99], 16, v199
	v_cmp_gt_i32_e64 s[100:101], -15, v199
	v_cmp_gt_i32_e64 vcc, 17, v199
	v_cndmask_b32_e64 v84, v84, v191, s[22:23]
	v_cndmask_b32_e64 v68, v68, v191, s[98:99]
	v_cndmask_b32_e64 v85, v85, v191, s[100:101]
	v_cndmask_b32_e64 v69, v69, v191, vcc
	v_cmp_gt_i32_e64 s[22:23], -14, v199
	v_cmp_gt_i32_e64 s[98:99], 18, v199
	v_cmp_gt_i32_e64 s[100:101], -13, v199
	v_cmp_gt_i32_e64 vcc, 19, v199
	v_cndmask_b32_e64 v86, v86, v191, s[22:23]
	v_cndmask_b32_e64 v70, v70, v191, s[98:99]
	v_cndmask_b32_e64 v87, v87, v191, s[100:101]
	v_cndmask_b32_e64 v71, v71, v191, vcc
	v_cmp_gt_i32_e64 s[22:23], -8, v199
	v_cmp_gt_i32_e64 s[98:99], 24, v199
	v_cmp_gt_i32_e64 s[100:101], -7, v199
	v_cmp_gt_i32_e64 vcc, 25, v199
	v_cndmask_b32_e64 v88, v88, v191, s[22:23]
	v_cndmask_b32_e64 v72, v72, v191, s[98:99]
	v_cndmask_b32_e64 v89, v89, v191, s[100:101]
	v_cndmask_b32_e64 v73, v73, v191, vcc
	v_cmp_gt_i32_e64 s[22:23], -6, v199
	v_cmp_gt_i32_e64 s[98:99], 26, v199
	v_cmp_gt_i32_e64 s[100:101], -5, v199
	v_cmp_gt_i32_e64 vcc, 27, v199
	v_cndmask_b32_e64 v90, v90, v191, s[22:23]
	v_cndmask_b32_e64 v74, v74, v191, s[98:99]
	v_cndmask_b32_e64 v91, v91, v191, s[100:101]
	v_cndmask_b32_e64 v75, v75, v191, vcc
	v_cmp_gt_i32_e64 s[22:23], 0, v199
	v_cmp_gt_i32_e64 s[98:99], 32, v199
	v_cmp_gt_i32_e64 s[100:101], 1, v199
	v_cmp_gt_i32_e64 vcc, 33, v199
	v_cndmask_b32_e64 v92, v92, v191, s[22:23]
	v_cndmask_b32_e64 v76, v76, v191, s[98:99]
	v_cndmask_b32_e64 v93, v93, v191, s[100:101]
	v_cndmask_b32_e64 v77, v77, v191, vcc
	v_cmp_gt_i32_e64 s[22:23], 2, v199
	v_cmp_gt_i32_e64 s[98:99], 34, v199
	v_cmp_gt_i32_e64 s[100:101], 3, v199
	v_cmp_gt_i32_e64 vcc, 35, v199
	v_cndmask_b32_e64 v94, v94, v191, s[22:23]
	v_cndmask_b32_e64 v78, v78, v191, s[98:99]
	v_cndmask_b32_e64 v95, v95, v191, s[100:101]
	v_cndmask_b32_e64 v79, v79, v191, vcc
	v_cmp_gt_i32_e64 s[22:23], 8, v199
	v_cmp_gt_i32_e64 s[98:99], 40, v199
	v_cmp_gt_i32_e64 s[100:101], 9, v199
	v_cmp_gt_i32_e64 vcc, 41, v199
	v_cndmask_b32_e64 v96, v96, v191, s[22:23]
	v_cndmask_b32_e64 v80, v80, v191, s[98:99]
	v_cndmask_b32_e64 v97, v97, v191, s[100:101]
	v_cndmask_b32_e64 v81, v81, v191, vcc
	v_cmp_gt_i32_e64 s[22:23], 10, v199
	v_cmp_gt_i32_e64 s[98:99], 42, v199
	v_cmp_gt_i32_e64 s[100:101], 11, v199
	v_cmp_gt_i32_e64 vcc, 43, v199
	v_cndmask_b32_e64 v98, v98, v191, s[22:23]
	v_cndmask_b32_e64 v82, v82, v191, s[98:99]
	v_cndmask_b32_e64 v99, v99, v191, s[100:101]
	v_cndmask_b32_e64 v83, v83, v191, vcc

; #define SBAR() __builtin_amdgcn_sched_barrier(0)
; #define QK_RD(d0, sl) do { if ((d0) < 8) { const int a_ = kbase ^ (((d0) & 7) << 5); KRD(f0[sl], a_, 0); KRD(f1[sl], a_, 32 * 256); } \
;                            else { const int a_ = rbase ^ (((d0) & 3) << 5); KRD(f0[sl], a_, 0); KRD(f1[sl], a_, 32 * 128); } } while (0)
; #define PV_RD(d0, L, H) do { constexpr int b_ = v_rd_off(d0, 0, 0); TRRD(L[0], b_); TRRD(H[0], b_ + 2048); TRRD(L[1], b_ + 4096); TRRD(H[1], b_ + 6144); TRRD(L[2], b_ + 8192); TRRD(H[2], b_ + 10240); TRRD(L[3], b_ + 12288); TRRD(H[3], b_ + 14336); } while (0)
; #define LGKM(n) asm volatile("s_waitcnt lgkmcnt(" #n ")" ::: "memory")
; __device__ __forceinline__ void mphase(bool has_pv, f32x16* o, int vb, bf16x8 pa0, bf16x8 pa1, bf16x8 pa2, bf16x8 pa3, f32x16& p0, f32x16& p1, int kbase, int rbase, const bf16x8* qr) {
;     ...
;     if (has_pv) {
;         s16x4 la[4], ha[4], lb[4], hb[4];
;         PV_RD(0, la, ha); PV_RD(1, lb, hb);
;         LGKM(8); SBAR(); PV_MM(0, la, ha); SBAR();
;         PV_RD(2, la, ha); LGKM(8); SBAR(); PV_MM(1, lb, hb); SBAR();
;         PV_RD(3, lb, hb); LGKM(8); SBAR(); PV_MM(2, la, ha); SBAR();
;         LGKM(0); SBAR(); PV_MM(3, lb, hb); SBAR();
;     ...
;     QK_RD(0, 0); QK_RD(1, 1);
;     p0 = f32x16{}; p1 = f32x16{};
; #pragma unroll
;     for (int d0 = 0; d0 < 12; ++d0) {
;         if (d0 + 2 < 12) { QK_RD(d0 + 2, (d0 + 2) % 3); LGKM(4); }
;         else if (d0 + 1 < 12) LGKM(2);
;         else LGKM(0);
;         SBAR();
;         p0 = __builtin_amdgcn_mfma_f32_32x32x16_bf16(f0[d0 % 3], qr[d0], p0, 0, 0, 0);
;         p1 = __builtin_amdgcn_mfma_f32_32x32x16_bf16(f1[d0 % 3], qr[d0], p1, 0, 0, 0);
;         SBAR(); }
.Lattn_qk_h:
	s_waitcnt lgkmcnt(4)
	v_mfma_f32_32x32x16_bf16 v[84:99], v[68:71], v[100:103], v[224:239]
	v_xor_b32_e32 v199, 0x60, v3
	ds_read_b128 v[216:219], v199 offset:0
	ds_read_b128 v[220:223], v199 offset:0x2000
	s_waitcnt lgkmcnt(4)
	v_mfma_f32_32x32x16_bf16 v[84:99], v[200:203], v[104:107], v[84:99]
	v_xor_b32_e32 v199, 0x80, v3
	ds_read_b128 v[200:203], v199 offset:0
	ds_read_b128 v[204:207], v199 offset:0x2000
	s_waitcnt lgkmcnt(4)
	v_mfma_f32_32x32x16_bf16 v[84:99], v[208:211], v[108:111], v[84:99]
	v_xor_b32_e32 v199, 0xa0, v3
	ds_read_b128 v[208:211], v199 offset:0
	ds_read_b128 v[212:215], v199 offset:0x2000
	s_waitcnt lgkmcnt(4)
	v_mfma_f32_32x32x16_bf16 v[84:99], v[216:219], v[112:115], v[84:99]
	v_xor_b32_e32 v199, 0xc0, v3
	ds_read_b128 v[216:219], v199 offset:0
	ds_read_b128 v[220:223], v199 offset:0x2000
	s_waitcnt lgkmcnt(4)
	v_mfma_f32_32x32x16_bf16 v[84:99], v[200:203], v[116:119], v[84:99]
	v_xor_b32_e32 v199, 0xe0, v3
	ds_read_b128 v[200:203], v199 offset:0
	ds_read_b128 v[204:207], v199 offset:0x2000
	s_waitcnt lgkmcnt(4)
	v_mfma_f32_32x32x16_bf16 v[84:99], v[208:211], v[120:123], v[84:99]
	ds_read_b128 v[208:211], v197 offset:0
	ds_read_b128 v[212:215], v197 offset:0x1000
	s_waitcnt lgkmcnt(4)
	v_mfma_f32_32x32x16_bf16 v[84:99], v[216:219], v[124:127], v[84:99]
	v_xor_b32_e32 v199, 32, v197
	ds_read_b128 v[216:219], v199 offset:0
	ds_read_b128 v[220:223], v199 offset:0x1000
	s_waitcnt lgkmcnt(4)
	v_mfma_f32_32x32x16_bf16 v[84:99], v[200:203], v[128:131], v[84:99]
	v_xor_b32_e32 v199, 64, v197
	ds_read_b128 v[200:203], v199 offset:0
	ds_read_b128 v[204:207], v199 offset:0x1000
	s_waitcnt lgkmcnt(4)
	v_mfma_f32_32x32x16_bf16 v[84:99], v[208:211], v[132:135], v[84:99]
	v_xor_b32_e32 v199, 0x60, v197
	ds_read_b128 v[208:211], v199 offset:0
	ds_read_b128 v[212:215], v199 offset:0x1000
	s_waitcnt lgkmcnt(4)
	v_mfma_f32_32x32x16_bf16 v[84:99], v[216:219], v[136:139], v[84:99]
	s_waitcnt lgkmcnt(2)
	v_mfma_f32_32x32x16_bf16 v[84:99], v[200:203], v[140:143], v[84:99]
	s_waitcnt lgkmcnt(0)
	v_mfma_f32_32x32x16_bf16 v[84:99], v[208:211], v[144:147], v[84:99]
	s_branch .Lattn_qk_end
.Lattn_pv_h:
	v_lshl_add_u32 v199, s83, 14, v182
	ds_read_b64_tr_b16 v[84:85], v199 offset:0x0
	ds_read_b64_tr_b16 v[86:87], v199 offset:0x800
	ds_read_b64_tr_b16 v[88:89], v199 offset:0x1000
	ds_read_b64_tr_b16 v[90:91], v199 offset:0x1800
	ds_read_b64_tr_b16 v[92:93], v199 offset:0x2000
	ds_read_b64_tr_b16 v[94:95], v199 offset:0x2800
	ds_read_b64_tr_b16 v[96:97], v199 offset:0x3000
	ds_read_b64_tr_b16 v[98:99], v199 offset:0x3800
	s_waitcnt lgkmcnt(6)
	v_mfma_f32_32x32x16_bf16 v[52:67], v[68:71], v[84:87], v[52:67]
	ds_read_b64_tr_b16 v[200:201], v199 offset:0x200
	ds_read_b64_tr_b16 v[202:203], v199 offset:0xa00
	s_waitcnt lgkmcnt(6)
	v_mfma_f32_32x32x16_bf16 v[52:67], v[72:75], v[88:91], v[52:67]
	ds_read_b64_tr_b16 v[204:205], v199 offset:0x1200
	ds_read_b64_tr_b16 v[206:207], v199 offset:0x1a00
	s_waitcnt lgkmcnt(6)
	ds_read_b64_tr_b16 v[208:209], v199 offset:0x2200
	ds_read_b64_tr_b16 v[210:211], v199 offset:0x2a00
	s_waitcnt lgkmcnt(6)
	ds_read_b64_tr_b16 v[212:213], v199 offset:0x3200
	ds_read_b64_tr_b16 v[214:215], v199 offset:0x3a00
	ds_read_b64_tr_b16 v[84:85], v199 offset:0x400
	ds_read_b64_tr_b16 v[86:87], v199 offset:0xc00
	s_waitcnt lgkmcnt(8)
	v_mfma_f32_32x32x16_bf16 v[36:51], v[68:71], v[200:203], v[36:51]
	ds_read_b64_tr_b16 v[88:89], v199 offset:0x1400
	ds_read_b64_tr_b16 v[90:91], v199 offset:0x1c00
	s_waitcnt lgkmcnt(8)
	v_mfma_f32_32x32x16_bf16 v[36:51], v[72:75], v[204:207], v[36:51]
	ds_read_b64_tr_b16 v[92:93], v199 offset:0x2400
	ds_read_b64_tr_b16 v[94:95], v199 offset:0x2c00
	s_waitcnt lgkmcnt(8)
	ds_read_b64_tr_b16 v[96:97], v199 offset:0x3400
	ds_read_b64_tr_b16 v[98:99], v199 offset:0x3c00
	s_waitcnt lgkmcnt(8)
	ds_read_b64_tr_b16 v[200:201], v199 offset:0x600
	ds_read_b64_tr_b16 v[202:203], v199 offset:0xe00
	s_waitcnt lgkmcnt(8)
	v_mfma_f32_32x32x16_bf16 v[20:35], v[68:71], v[84:87], v[20:35]
	ds_read_b64_tr_b16 v[204:205], v199 offset:0x1600
	ds_read_b64_tr_b16 v[206:207], v199 offset:0x1e00
	s_waitcnt lgkmcnt(8)
	v_mfma_f32_32x32x16_bf16 v[20:35], v[72:75], v[88:91], v[20:35]
	ds_read_b64_tr_b16 v[208:209], v199 offset:0x2600
	ds_read_b64_tr_b16 v[210:211], v199 offset:0x2e00
	s_waitcnt lgkmcnt(8)
	ds_read_b64_tr_b16 v[212:213], v199 offset:0x3600
	ds_read_b64_tr_b16 v[214:215], v199 offset:0x3e00
	s_waitcnt lgkmcnt(8)
	s_waitcnt lgkmcnt(6)
	v_mfma_f32_32x32x16_bf16 v[4:19], v[68:71], v[200:203], v[4:19]
	ds_read_b128 v[68:71], v3 offset:0
	s_waitcnt lgkmcnt(5)
	v_mfma_f32_32x32x16_bf16 v[4:19], v[72:75], v[204:207], v[4:19]
	ds_read_b128 v[72:75], v3 offset:0x2000
	v_xor_b32_e32 v199, 32, v3
	ds_read_b128 v[200:203], v199 offset:0
	s_waitcnt lgkmcnt(5)
	ds_read_b128 v[204:207], v199 offset:0x2000
	s_waitcnt lgkmcnt(4)
	v_xor_b32_e32 v76, 64, v3
	ds_read_b128 v[208:211], v76 offset:0
	ds_read_b128 v[212:215], v76 offset:0x2000
	s_branch .Lattn_dead_qk
; #define SBAR() __builtin_amdgcn_sched_barrier(0)
; __device__ __forceinline__ void pv_tile(f32x16* o, int vb, bf16x8 pa0, bf16x8 pa1, bf16x8 pa2, bf16x8 pa3) {
;     ...
;     PV_D0(0); PV_D0(1); PV_D0(2); PV_D0(3);
; __device__ __forceinline__ void attn_block(const Ptrs& P, int b, int h, int qb, LAS char* lds) {
;     ...
;     SBAR(); __builtin_amdgcn_s_setprio(1); pv_tile(o, vb0 + pv3 * SHM_V, pa0, pa1, pa2, pa3); __builtin_amdgcn_s_setprio(0); SBAR();
.Lattn_flush_h:
	s_setprio 1
	v_lshl_add_u32 v3, s83, 14, v182
	ds_read_b64_tr_b16 v[86:87], v3 offset:0
	ds_read_b64_tr_b16 v[88:89], v3 offset:0x800
	ds_read_b64_tr_b16 v[90:91], v3 offset:0x1000
	ds_read_b64_tr_b16 v[92:93], v3 offset:0x1800
	ds_read_b64_tr_b16 v[94:95], v3 offset:0x2000
	ds_read_b64_tr_b16 v[96:97], v3 offset:0x2800
	ds_read_b64_tr_b16 v[98:99], v3 offset:0x3000
	ds_read_b64_tr_b16 v[100:101], v3 offset:0x3800
	s_waitcnt lgkmcnt(0)
	s_nop 0
	v_mfma_f32_32x32x16_bf16 v[52:67], v[68:71], v[86:89], v[52:67]
	ds_read_b64_tr_b16 v[86:87], v3 offset:0x200
	ds_read_b64_tr_b16 v[88:89], v3 offset:0xa00
	v_mfma_f32_32x32x16_bf16 v[52:67], v[72:75], v[90:93], v[52:67]
	ds_read_b64_tr_b16 v[90:91], v3 offset:0x1200
	ds_read_b64_tr_b16 v[92:93], v3 offset:0x1a00
	ds_read_b64_tr_b16 v[94:95], v3 offset:0x2200
	ds_read_b64_tr_b16 v[96:97], v3 offset:0x2a00
	ds_read_b64_tr_b16 v[102:103], v3 offset:0x3200
	ds_read_b64_tr_b16 v[104:105], v3 offset:0x3a00
	s_waitcnt lgkmcnt(0)
	v_mfma_f32_32x32x16_bf16 v[36:51], v[68:71], v[86:89], v[36:51]
	ds_read_b64_tr_b16 v[86:87], v3 offset:0x400
	ds_read_b64_tr_b16 v[88:89], v3 offset:0xc00
	v_mfma_f32_32x32x16_bf16 v[36:51], v[72:75], v[90:93], v[36:51]
	ds_read_b64_tr_b16 v[90:91], v3 offset:0x1400
	ds_read_b64_tr_b16 v[92:93], v3 offset:0x1c00
	ds_read_b64_tr_b16 v[94:95], v3 offset:0x2400
	ds_read_b64_tr_b16 v[96:97], v3 offset:0x2c00
	ds_read_b64_tr_b16 v[98:99], v3 offset:0x3400
	ds_read_b64_tr_b16 v[100:101], v3 offset:0x3c00
	s_waitcnt lgkmcnt(0)
	v_mfma_f32_32x32x16_bf16 v[20:35], v[68:71], v[86:89], v[20:35]
	ds_read_b64_tr_b16 v[86:87], v3 offset:0x600
	ds_read_b64_tr_b16 v[88:89], v3 offset:0xe00
	v_mfma_f32_32x32x16_bf16 v[20:35], v[72:75], v[90:93], v[20:35]
	ds_read_b64_tr_b16 v[90:91], v3 offset:0x1600
	ds_read_b64_tr_b16 v[92:93], v3 offset:0x1e00
	ds_read_b64_tr_b16 v[94:95], v3 offset:0x2600
	ds_read_b64_tr_b16 v[96:97], v3 offset:0x2e00
	ds_read_b64_tr_b16 v[102:103], v3 offset:0x3600
	ds_read_b64_tr_b16 v[104:105], v3 offset:0x3e00
	s_waitcnt lgkmcnt(0)
	v_mfma_f32_32x32x16_bf16 v[4:19], v[68:71], v[86:89], v[4:19]
	v_mfma_f32_32x32x16_bf16 v[4:19], v[72:75], v[90:93], v[4:19]
	s_setprio 0
	s_branch .Lattn_dead_flush
.LBB0_629:
	v_mov_b32_e32 v85, v198
	v_mov_b32_e32 v86, v198
	s_nop 1
	v_permlane32_swap_b32_e32 v85, v86
	v_add_f32_e32 v85, v85, v86
	s_add_i32 s22, s75, s81
	s_cmp_lt_i32 s22, -95
	s_cbranch_scc1 .Lattn_dead_flush
	s_cmp_lt_i32 s22, -63
	s_cbranch_scc1 .Lattn_flush_h
	s_setprio 1
	v_lshl_add_u32 v3, s83, 14, v182
	ds_read_b64_tr_b16 v[86:87], v3 offset:0
	ds_read_b64_tr_b16 v[88:89], v3 offset:0x800
	ds_read_b64_tr_b16 v[90:91], v3 offset:0x1000
	ds_read_b64_tr_b16 v[92:93], v3 offset:0x1800
	ds_read_b64_tr_b16 v[94:95], v3 offset:0x2000
	ds_read_b64_tr_b16 v[96:97], v3 offset:0x2800
	ds_read_b64_tr_b16 v[98:99], v3 offset:0x3000
	ds_read_b64_tr_b16 v[100:101], v3 offset:0x3800
	s_waitcnt lgkmcnt(0)
	s_nop 0
	v_mfma_f32_32x32x16_bf16 v[52:67], v[68:71], v[86:89], v[52:67]
	ds_read_b64_tr_b16 v[86:87], v3 offset:0x200
	ds_read_b64_tr_b16 v[88:89], v3 offset:0xa00
	v_mfma_f32_32x32x16_bf16 v[52:67], v[72:75], v[90:93], v[52:67]
	ds_read_b64_tr_b16 v[90:91], v3 offset:0x1200
	ds_read_b64_tr_b16 v[92:93], v3 offset:0x1a00
	v_mfma_f32_32x32x16_bf16 v[52:67], v[76:79], v[94:97], v[52:67]
	ds_read_b64_tr_b16 v[94:95], v3 offset:0x2200
	ds_read_b64_tr_b16 v[96:97], v3 offset:0x2a00
	ds_read_b64_tr_b16 v[102:103], v3 offset:0x3200
	ds_read_b64_tr_b16 v[104:105], v3 offset:0x3a00
	s_waitcnt lgkmcnt(0)
	v_mfma_f32_32x32x16_bf16 v[52:67], v[80:83], v[98:101], v[52:67]
	v_mfma_f32_32x32x16_bf16 v[36:51], v[68:71], v[86:89], v[36:51]
	ds_read_b64_tr_b16 v[86:87], v3 offset:0x400
	ds_read_b64_tr_b16 v[88:89], v3 offset:0xc00
	v_mfma_f32_32x32x16_bf16 v[36:51], v[72:75], v[90:93], v[36:51]
	ds_read_b64_tr_b16 v[90:91], v3 offset:0x1400
	ds_read_b64_tr_b16 v[92:93], v3 offset:0x1c00
	v_mfma_f32_32x32x16_bf16 v[36:51], v[76:79], v[94:97], v[36:51]
	ds_read_b64_tr_b16 v[94:95], v3 offset:0x2400
	ds_read_b64_tr_b16 v[96:97], v3 offset:0x2c00
	ds_read_b64_tr_b16 v[98:99], v3 offset:0x3400
	ds_read_b64_tr_b16 v[100:101], v3 offset:0x3c00
	s_waitcnt lgkmcnt(0)
	v_mfma_f32_32x32x16_bf16 v[36:51], v[80:83], v[102:105], v[36:51]
	v_mfma_f32_32x32x16_bf16 v[20:35], v[68:71], v[86:89], v[20:35]
	ds_read_b64_tr_b16 v[86:87], v3 offset:0x600
	ds_read_b64_tr_b16 v[88:89], v3 offset:0xe00
	v_mfma_f32_32x32x16_bf16 v[20:35], v[72:75], v[90:93], v[20:35]
	ds_read_b64_tr_b16 v[90:91], v3 offset:0x1600
	ds_read_b64_tr_b16 v[92:93], v3 offset:0x1e00
	v_mfma_f32_32x32x16_bf16 v[20:35], v[76:79], v[94:97], v[20:35]
	ds_read_b64_tr_b16 v[94:95], v3 offset:0x2600
	ds_read_b64_tr_b16 v[96:97], v3 offset:0x2e00
	ds_read_b64_tr_b16 v[102:103], v3 offset:0x3600
	ds_read_b64_tr_b16 v[104:105], v3 offset:0x3e00
	s_waitcnt lgkmcnt(0)
	v_mfma_f32_32x32x16_bf16 v[20:35], v[80:83], v[98:101], v[20:35]
	v_mfma_f32_32x32x16_bf16 v[4:19], v[68:71], v[86:89], v[4:19]
	v_mfma_f32_32x32x16_bf16 v[4:19], v[72:75], v[90:93], v[4:19]
	v_mfma_f32_32x32x16_bf16 v[4:19], v[76:79], v[94:97], v[4:19]
	v_mfma_f32_32x32x16_bf16 v[4:19], v[80:83], v[102:105], v[4:19]
	s_setprio 0
